# as v007 + counted lgkmcnt(2) before the first PV MFMA (do not wait for the wave's own K/V tile ds_writes)
# speedup vs baseline: 1.0053x; 1.0053x over previous
.LBB0_747:
	v_exp_f32_e32 v192, v64
	v_exp_f32_e32 v193, v65
	v_exp_f32_e32 v194, v66
	v_exp_f32_e32 v195, v67
	v_exp_f32_e32 v196, v68
	v_exp_f32_e32 v197, v69
	v_exp_f32_e32 v198, v70
	v_exp_f32_e32 v199, v71
	v_cvt_pk_bf16_f32 v64, v192, v193
	v_cvt_pk_bf16_f32 v65, v194, v195
	v_cvt_pk_bf16_f32 v66, v196, v197
	v_cvt_pk_bf16_f32 v67, v198, v199
	v_exp_f32_e32 v72, v72
	v_exp_f32_e32 v73, v73
	v_exp_f32_e32 v74, v74
	v_exp_f32_e32 v75, v75
	v_exp_f32_e32 v76, v76
	v_exp_f32_e32 v77, v77
	v_exp_f32_e32 v78, v78
	v_exp_f32_e32 v79, v79
	s_waitcnt lgkmcnt(2)
	v_mfma_f32_32x32x16_bf16 v[0:15], v[64:67], v[160:163], v[0:15]
	v_cvt_pk_bf16_f32 v68, v72, v73
	v_cvt_pk_bf16_f32 v69, v74, v75
	v_cvt_pk_bf16_f32 v70, v76, v77
	v_cvt_pk_bf16_f32 v71, v78, v79
	v_exp_f32_e32 v200, v48
	v_exp_f32_e32 v201, v49
	v_exp_f32_e32 v52, v52
	v_mfma_f32_32x32x16_bf16 v[16:31], v[64:67], v[156:159], v[16:31]
	v_exp_f32_e32 v64, v50
	v_exp_f32_e32 v65, v51
	v_exp_f32_e32 v53, v53
	v_exp_f32_e32 v66, v54
	v_exp_f32_e32 v67, v55
	v_cvt_pk_bf16_f32 v48, v200, v201
	v_cvt_pk_bf16_f32 v49, v64, v65
	v_mfma_f32_32x32x16_bf16 v[0:15], v[68:71], v[152:155], v[0:15]
	v_cvt_pk_bf16_f32 v50, v52, v53
	v_cvt_pk_bf16_f32 v51, v66, v67
	v_add_f32_e64 v54, v192, 0
	v_add_f32_e64 v55, v193, 0
	v_exp_f32_e32 v56, v56
	v_exp_f32_e32 v57, v57
	v_exp_f32_e32 v58, v58
	v_exp_f32_e32 v59, v59
	v_mfma_f32_32x32x16_bf16 v[16:31], v[68:71], v[148:151], v[16:31]
	v_exp_f32_e32 v60, v60
	v_exp_f32_e32 v61, v61
	v_exp_f32_e32 v62, v62
	v_exp_f32_e32 v63, v63
	v_pk_add_f32 v[54:55], v[200:201], v[54:55]
	s_nop 0
	v_pk_add_f32 v[54:55], v[194:195], v[54:55]
	v_mfma_f32_32x32x16_bf16 v[0:15], v[48:51], v[144:147], v[0:15]
	v_add_f32_e64 v54, v64, v54
	v_add_f32_e64 v55, v65, v55
	v_add_f32_e64 v54, v196, v54
	v_add_f32_e64 v55, v197, v55
	v_add_f32_e64 v64, v52, v54
	v_add_f32_e64 v65, v53, v55
	v_cvt_pk_bf16_f32 v52, v56, v57
	v_cvt_pk_bf16_f32 v53, v58, v59
	v_mfma_f32_32x32x16_bf16 v[16:31], v[48:51], v[140:143], v[16:31]
	v_cvt_pk_bf16_f32 v54, v60, v61
	v_cvt_pk_bf16_f32 v55, v62, v63
	v_add_f32_e64 v48, v198, v64
	v_add_f32_e64 v49, v199, v65
	v_add_f32_e64 v48, v66, v48
	v_add_f32_e64 v49, v67, v49
	v_pk_add_f32 v[48:49], v[72:73], v[48:49]
	v_mfma_f32_32x32x16_bf16 v[0:15], v[52:55], v[136:139], v[0:15]
	v_add_f32_e64 v48, v56, v48
	v_add_f32_e64 v49, v57, v49
	v_add_f32_e64 v48, v74, v48
	v_add_f32_e64 v49, v75, v49
	v_add_f32_e64 v48, v58, v48
	v_add_f32_e64 v49, v59, v49
	v_pk_add_f32 v[48:49], v[76:77], v[48:49]
	v_mfma_f32_32x32x16_bf16 v[16:31], v[52:55], v[132:135], v[16:31]
	v_add_f32_e64 v48, v60, v48
	v_add_f32_e64 v49, v61, v49
	v_add_f32_e64 v48, v78, v48
	v_add_f32_e64 v49, v79, v49
	v_add_f32_e64 v48, v62, v48
	v_add_f32_e64 v49, v63, v49
	v_add_f32_e32 v48, v48, v49
	v_add_f32_e32 v83, v83, v48
